# stepper: y-flush LDS reads issued early and consumed one slot later; chunk-exit scaling overlapped with second flush
# baseline (speedup 1.0000x reference)
.Lst_chunk:
	v_add_u32_e32 v132, s75, v140
	v_add_u32_e32 v133, s75, v141
	ds_read_b128 v[40:43], v132 offset:256
	ds_read_b128 v[44:47], v132 offset:272
	ds_read_b128 v[48:51], v132 offset:512
	ds_read_b128 v[52:55], v132 offset:528
	ds_read_b128 v[56:59], v132 offset:768
	ds_read_b128 v[60:63], v132 offset:784
	ds_read_b128 v[64:67], v132 offset:1024
	ds_read_b128 v[68:71], v132 offset:1040
	ds_read_b64 v[72:73], v133 offset:1280
	ds_read_b128 v[74:77], v132 offset:1808
	ds_read_b128 v[78:81], v132 offset:1824
	ds_read_b128 v[82:85], v132 offset:2064
	ds_read_b128 v[86:89], v132 offset:2080
	ds_read_b128 v[90:93], v132 offset:2320
	ds_read_b128 v[94:97], v132 offset:2336
	ds_read_b128 v[98:101], v132 offset:2576
	ds_read_b128 v[102:105], v132 offset:2592
	ds_read_b64 v[106:107], v133 offset:2832
	s_waitcnt lgkmcnt(15)
	v_pk_mul_f32 v[32:33], v[0:1], v[40:41] op_sel_hi:[1,0]
	v_pk_mul_f32 v[34:35], v[2:3], v[40:41] op_sel:[0,1]
	v_pk_fma_f32 v[32:33], v[4:5], v[42:43], v[32:33] op_sel_hi:[1,0,1]
	v_pk_fma_f32 v[34:35], v[6:7], v[42:43], v[34:35] op_sel:[0,1,0]
	v_pk_fma_f32 v[32:33], v[8:9], v[44:45], v[32:33] op_sel_hi:[1,0,1]
	v_pk_fma_f32 v[34:35], v[10:11], v[44:45], v[34:35] op_sel:[0,1,0]
	v_pk_fma_f32 v[32:33], v[12:13], v[46:47], v[32:33] op_sel_hi:[1,0,1]
	v_pk_fma_f32 v[34:35], v[14:15], v[46:47], v[34:35] op_sel:[0,1,0]
	v_pk_add_f32 v[32:33], v[32:33], v[34:35]
	s_nop 1
	s_waitcnt lgkmcnt(9)
	v_add_f32_dpp v32, v32, v32 row_half_mirror row_mask:0xf bank_mask:0xf bound_ctrl:1
	v_add_f32_dpp v33, v33, v33 row_half_mirror row_mask:0xf bank_mask:0xf bound_ctrl:1
	v_pk_fma_f32 v[16:17], v[72:73], v[56:57], v[0:1] op_sel_hi:[1,0,1]
	v_add_f32_dpp v32, v32, v32 quad_perm:[1,0,3,2] row_mask:0xf bank_mask:0xf bound_ctrl:1
	v_add_f32_dpp v33, v33, v33 quad_perm:[1,0,3,2] row_mask:0xf bank_mask:0xf bound_ctrl:1
	v_pk_fma_f32 v[18:19], v[72:73], v[56:57], v[2:3] op_sel:[0,1,0]
	v_add_f32_dpp v32, v32, v32 quad_perm:[2,3,0,1] row_mask:0xf bank_mask:0xf bound_ctrl:1
	v_add_f32_dpp v33, v33, v33 quad_perm:[2,3,0,1] row_mask:0xf bank_mask:0xf bound_ctrl:1
	v_pk_fma_f32 v[20:21], v[72:73], v[58:59], v[4:5] op_sel_hi:[1,0,1]
	v_pk_fma_f32 v[22:23], v[72:73], v[58:59], v[6:7] op_sel:[0,1,0]
	v_pk_fma_f32 v[24:25], v[72:73], v[60:61], v[8:9] op_sel_hi:[1,0,1]
	v_pk_fma_f32 v[26:27], v[72:73], v[60:61], v[10:11] op_sel:[0,1,0]
	v_pk_fma_f32 v[28:29], v[72:73], v[62:63], v[12:13] op_sel_hi:[1,0,1]
	v_pk_fma_f32 v[30:31], v[72:73], v[62:63], v[14:15] op_sel:[0,1,0]
	v_pk_fma_f32 v[0:1], v[32:33], v[48:49], v[16:17] op_sel_hi:[1,0,1]
	v_pk_fma_f32 v[2:3], v[32:33], v[48:49], v[18:19] op_sel:[0,1,0]
	v_pk_fma_f32 v[4:5], v[32:33], v[50:51], v[20:21] op_sel_hi:[1,0,1]
	v_pk_fma_f32 v[6:7], v[32:33], v[50:51], v[22:23] op_sel:[0,1,0]
	v_pk_fma_f32 v[8:9], v[32:33], v[52:53], v[24:25] op_sel_hi:[1,0,1]
	v_pk_fma_f32 v[10:11], v[32:33], v[52:53], v[26:27] op_sel:[0,1,0]
	v_pk_fma_f32 v[12:13], v[32:33], v[54:55], v[28:29] op_sel_hi:[1,0,1]
	v_pk_fma_f32 v[14:15], v[32:33], v[54:55], v[30:31] op_sel:[0,1,0]
	s_waitcnt lgkmcnt(7)
	v_pk_mul_f32 v[32:33], v[0:1], v[74:75] op_sel_hi:[1,0]
	v_pk_mul_f32 v[36:37], v[0:1], v[64:65] op_sel_hi:[1,0]
	v_pk_mul_f32 v[34:35], v[2:3], v[74:75] op_sel:[0,1]
	v_pk_mul_f32 v[38:39], v[2:3], v[64:65] op_sel:[0,1]
	v_pk_fma_f32 v[32:33], v[4:5], v[76:77], v[32:33] op_sel_hi:[1,0,1]
	v_pk_fma_f32 v[36:37], v[4:5], v[66:67], v[36:37] op_sel_hi:[1,0,1]
	v_pk_fma_f32 v[34:35], v[6:7], v[76:77], v[34:35] op_sel:[0,1,0]
	v_pk_fma_f32 v[38:39], v[6:7], v[66:67], v[38:39] op_sel:[0,1,0]
	v_pk_fma_f32 v[32:33], v[8:9], v[78:79], v[32:33] op_sel_hi:[1,0,1]
	v_pk_fma_f32 v[36:37], v[8:9], v[68:69], v[36:37] op_sel_hi:[1,0,1]
	v_pk_fma_f32 v[34:35], v[10:11], v[78:79], v[34:35] op_sel:[0,1,0]
	v_pk_fma_f32 v[38:39], v[10:11], v[68:69], v[38:39] op_sel:[0,1,0]
	v_pk_fma_f32 v[32:33], v[12:13], v[80:81], v[32:33] op_sel_hi:[1,0,1]
	v_pk_fma_f32 v[36:37], v[12:13], v[70:71], v[36:37] op_sel_hi:[1,0,1]
	v_pk_fma_f32 v[34:35], v[14:15], v[80:81], v[34:35] op_sel:[0,1,0]
	v_pk_fma_f32 v[38:39], v[14:15], v[70:71], v[38:39] op_sel:[0,1,0]
	v_pk_add_f32 v[36:37], v[36:37], v[38:39]
	v_pk_add_f32 v[32:33], v[32:33], v[34:35]
	ds_write2st64_b32 v134, v36, v37 offset0:0 offset1:1
	ds_read_b128 v[40:43], v132 offset:3360
	ds_read_b128 v[44:47], v132 offset:3376
	ds_read_b128 v[48:51], v132 offset:3616
	ds_read_b128 v[52:55], v132 offset:3632
	ds_read_b128 v[56:59], v132 offset:3872
	ds_read_b128 v[60:63], v132 offset:3888
	ds_read_b128 v[64:67], v132 offset:4128
	ds_read_b128 v[68:71], v132 offset:4144
	ds_read_b64 v[72:73], v133 offset:4384
	s_waitcnt lgkmcnt(10)
	v_add_f32_dpp v32, v32, v32 row_half_mirror row_mask:0xf bank_mask:0xf bound_ctrl:1
	v_add_f32_dpp v33, v33, v33 row_half_mirror row_mask:0xf bank_mask:0xf bound_ctrl:1
	v_pk_fma_f32 v[16:17], v[106:107], v[90:91], v[0:1] op_sel_hi:[1,0,1]
	v_add_f32_dpp v32, v32, v32 quad_perm:[1,0,3,2] row_mask:0xf bank_mask:0xf bound_ctrl:1
	v_add_f32_dpp v33, v33, v33 quad_perm:[1,0,3,2] row_mask:0xf bank_mask:0xf bound_ctrl:1
	v_pk_fma_f32 v[18:19], v[106:107], v[90:91], v[2:3] op_sel:[0,1,0]
	v_add_f32_dpp v32, v32, v32 quad_perm:[2,3,0,1] row_mask:0xf bank_mask:0xf bound_ctrl:1
	v_add_f32_dpp v33, v33, v33 quad_perm:[2,3,0,1] row_mask:0xf bank_mask:0xf bound_ctrl:1
	v_pk_fma_f32 v[20:21], v[106:107], v[92:93], v[4:5] op_sel_hi:[1,0,1]
	v_pk_fma_f32 v[22:23], v[106:107], v[92:93], v[6:7] op_sel:[0,1,0]
	v_pk_fma_f32 v[24:25], v[106:107], v[94:95], v[8:9] op_sel_hi:[1,0,1]
	v_pk_fma_f32 v[26:27], v[106:107], v[94:95], v[10:11] op_sel:[0,1,0]
	v_pk_fma_f32 v[28:29], v[106:107], v[96:97], v[12:13] op_sel_hi:[1,0,1]
	v_pk_fma_f32 v[30:31], v[106:107], v[96:97], v[14:15] op_sel:[0,1,0]
	v_pk_fma_f32 v[0:1], v[32:33], v[82:83], v[16:17] op_sel_hi:[1,0,1]
	v_pk_fma_f32 v[2:3], v[32:33], v[82:83], v[18:19] op_sel:[0,1,0]
	v_pk_fma_f32 v[4:5], v[32:33], v[84:85], v[20:21] op_sel_hi:[1,0,1]
	v_pk_fma_f32 v[6:7], v[32:33], v[84:85], v[22:23] op_sel:[0,1,0]
	v_pk_fma_f32 v[8:9], v[32:33], v[86:87], v[24:25] op_sel_hi:[1,0,1]
	v_pk_fma_f32 v[10:11], v[32:33], v[86:87], v[26:27] op_sel:[0,1,0]
	v_pk_fma_f32 v[12:13], v[32:33], v[88:89], v[28:29] op_sel_hi:[1,0,1]
	v_pk_fma_f32 v[14:15], v[32:33], v[88:89], v[30:31] op_sel:[0,1,0]
	s_waitcnt lgkmcnt(7)
	v_pk_mul_f32 v[32:33], v[0:1], v[40:41] op_sel_hi:[1,0]
	v_pk_mul_f32 v[36:37], v[0:1], v[98:99] op_sel_hi:[1,0]
	v_pk_mul_f32 v[34:35], v[2:3], v[40:41] op_sel:[0,1]
	v_pk_mul_f32 v[38:39], v[2:3], v[98:99] op_sel:[0,1]
	v_pk_fma_f32 v[32:33], v[4:5], v[42:43], v[32:33] op_sel_hi:[1,0,1]
	v_pk_fma_f32 v[36:37], v[4:5], v[100:101], v[36:37] op_sel_hi:[1,0,1]
	v_pk_fma_f32 v[34:35], v[6:7], v[42:43], v[34:35] op_sel:[0,1,0]
	v_pk_fma_f32 v[38:39], v[6:7], v[100:101], v[38:39] op_sel:[0,1,0]
	v_pk_fma_f32 v[32:33], v[8:9], v[44:45], v[32:33] op_sel_hi:[1,0,1]
	v_pk_fma_f32 v[36:37], v[8:9], v[102:103], v[36:37] op_sel_hi:[1,0,1]
	v_pk_fma_f32 v[34:35], v[10:11], v[44:45], v[34:35] op_sel:[0,1,0]
	v_pk_fma_f32 v[38:39], v[10:11], v[102:103], v[38:39] op_sel:[0,1,0]
	v_pk_fma_f32 v[32:33], v[12:13], v[46:47], v[32:33] op_sel_hi:[1,0,1]
	v_pk_fma_f32 v[36:37], v[12:13], v[104:105], v[36:37] op_sel_hi:[1,0,1]
	v_pk_fma_f32 v[34:35], v[14:15], v[46:47], v[34:35] op_sel:[0,1,0]
	v_pk_fma_f32 v[38:39], v[14:15], v[104:105], v[38:39] op_sel:[0,1,0]
	v_pk_add_f32 v[36:37], v[36:37], v[38:39]
	v_pk_add_f32 v[32:33], v[32:33], v[34:35]
	ds_write2st64_b32 v134, v36, v37 offset0:2 offset1:3
	ds_read_b128 v[74:77], v132 offset:4912
	ds_read_b128 v[78:81], v132 offset:4928
	ds_read_b128 v[82:85], v132 offset:5168
	ds_read_b128 v[86:89], v132 offset:5184
	ds_read_b128 v[90:93], v132 offset:5424
	ds_read_b128 v[94:97], v132 offset:5440
	ds_read_b128 v[98:101], v132 offset:5680
	ds_read_b128 v[102:105], v132 offset:5696
	ds_read_b64 v[106:107], v133 offset:5936
	s_waitcnt lgkmcnt(10)
	v_add_f32_dpp v32, v32, v32 row_half_mirror row_mask:0xf bank_mask:0xf bound_ctrl:1
	v_add_f32_dpp v33, v33, v33 row_half_mirror row_mask:0xf bank_mask:0xf bound_ctrl:1
	v_pk_fma_f32 v[16:17], v[72:73], v[56:57], v[0:1] op_sel_hi:[1,0,1]
	v_add_f32_dpp v32, v32, v32 quad_perm:[1,0,3,2] row_mask:0xf bank_mask:0xf bound_ctrl:1
	v_add_f32_dpp v33, v33, v33 quad_perm:[1,0,3,2] row_mask:0xf bank_mask:0xf bound_ctrl:1
	v_pk_fma_f32 v[18:19], v[72:73], v[56:57], v[2:3] op_sel:[0,1,0]
	v_add_f32_dpp v32, v32, v32 quad_perm:[2,3,0,1] row_mask:0xf bank_mask:0xf bound_ctrl:1
	v_add_f32_dpp v33, v33, v33 quad_perm:[2,3,0,1] row_mask:0xf bank_mask:0xf bound_ctrl:1
	v_pk_fma_f32 v[20:21], v[72:73], v[58:59], v[4:5] op_sel_hi:[1,0,1]
	v_pk_fma_f32 v[22:23], v[72:73], v[58:59], v[6:7] op_sel:[0,1,0]
	v_pk_fma_f32 v[24:25], v[72:73], v[60:61], v[8:9] op_sel_hi:[1,0,1]
	v_pk_fma_f32 v[26:27], v[72:73], v[60:61], v[10:11] op_sel:[0,1,0]
	v_pk_fma_f32 v[28:29], v[72:73], v[62:63], v[12:13] op_sel_hi:[1,0,1]
	v_pk_fma_f32 v[30:31], v[72:73], v[62:63], v[14:15] op_sel:[0,1,0]
	v_pk_fma_f32 v[0:1], v[32:33], v[48:49], v[16:17] op_sel_hi:[1,0,1]
	v_pk_fma_f32 v[2:3], v[32:33], v[48:49], v[18:19] op_sel:[0,1,0]
	v_pk_fma_f32 v[4:5], v[32:33], v[50:51], v[20:21] op_sel_hi:[1,0,1]
	v_pk_fma_f32 v[6:7], v[32:33], v[50:51], v[22:23] op_sel:[0,1,0]
	v_pk_fma_f32 v[8:9], v[32:33], v[52:53], v[24:25] op_sel_hi:[1,0,1]
	v_pk_fma_f32 v[10:11], v[32:33], v[52:53], v[26:27] op_sel:[0,1,0]
	v_pk_fma_f32 v[12:13], v[32:33], v[54:55], v[28:29] op_sel_hi:[1,0,1]
	v_pk_fma_f32 v[14:15], v[32:33], v[54:55], v[30:31] op_sel:[0,1,0]
	s_waitcnt lgkmcnt(7)
	v_pk_mul_f32 v[32:33], v[0:1], v[74:75] op_sel_hi:[1,0]
	v_pk_mul_f32 v[36:37], v[0:1], v[64:65] op_sel_hi:[1,0]
	v_pk_mul_f32 v[34:35], v[2:3], v[74:75] op_sel:[0,1]
	v_pk_mul_f32 v[38:39], v[2:3], v[64:65] op_sel:[0,1]
	v_pk_fma_f32 v[32:33], v[4:5], v[76:77], v[32:33] op_sel_hi:[1,0,1]
	v_pk_fma_f32 v[36:37], v[4:5], v[66:67], v[36:37] op_sel_hi:[1,0,1]
	v_pk_fma_f32 v[34:35], v[6:7], v[76:77], v[34:35] op_sel:[0,1,0]
	v_pk_fma_f32 v[38:39], v[6:7], v[66:67], v[38:39] op_sel:[0,1,0]
	v_pk_fma_f32 v[32:33], v[8:9], v[78:79], v[32:33] op_sel_hi:[1,0,1]
	v_pk_fma_f32 v[36:37], v[8:9], v[68:69], v[36:37] op_sel_hi:[1,0,1]
	v_pk_fma_f32 v[34:35], v[10:11], v[78:79], v[34:35] op_sel:[0,1,0]
	v_pk_fma_f32 v[38:39], v[10:11], v[68:69], v[38:39] op_sel:[0,1,0]
	v_pk_fma_f32 v[32:33], v[12:13], v[80:81], v[32:33] op_sel_hi:[1,0,1]
	v_pk_fma_f32 v[36:37], v[12:13], v[70:71], v[36:37] op_sel_hi:[1,0,1]
	v_pk_fma_f32 v[34:35], v[14:15], v[80:81], v[34:35] op_sel:[0,1,0]
	v_pk_fma_f32 v[38:39], v[14:15], v[70:71], v[38:39] op_sel:[0,1,0]
	v_pk_add_f32 v[36:37], v[36:37], v[38:39]
	v_pk_add_f32 v[32:33], v[32:33], v[34:35]
	ds_write2st64_b32 v134, v36, v37 offset0:4 offset1:5
	ds_read_b128 v[40:43], v132 offset:6464
	ds_read_b128 v[44:47], v132 offset:6480
	ds_read_b128 v[48:51], v132 offset:6720
	ds_read_b128 v[52:55], v132 offset:6736
	ds_read_b128 v[56:59], v132 offset:6976
	ds_read_b128 v[60:63], v132 offset:6992
	ds_read_b128 v[64:67], v132 offset:7232
	ds_read_b128 v[68:71], v132 offset:7248
	ds_read_b64 v[72:73], v133 offset:7488
	s_waitcnt lgkmcnt(10)
	v_add_f32_dpp v32, v32, v32 row_half_mirror row_mask:0xf bank_mask:0xf bound_ctrl:1
	v_add_f32_dpp v33, v33, v33 row_half_mirror row_mask:0xf bank_mask:0xf bound_ctrl:1
	v_pk_fma_f32 v[16:17], v[106:107], v[90:91], v[0:1] op_sel_hi:[1,0,1]
	v_add_f32_dpp v32, v32, v32 quad_perm:[1,0,3,2] row_mask:0xf bank_mask:0xf bound_ctrl:1
	v_add_f32_dpp v33, v33, v33 quad_perm:[1,0,3,2] row_mask:0xf bank_mask:0xf bound_ctrl:1
	v_pk_fma_f32 v[18:19], v[106:107], v[90:91], v[2:3] op_sel:[0,1,0]
	v_add_f32_dpp v32, v32, v32 quad_perm:[2,3,0,1] row_mask:0xf bank_mask:0xf bound_ctrl:1
	v_add_f32_dpp v33, v33, v33 quad_perm:[2,3,0,1] row_mask:0xf bank_mask:0xf bound_ctrl:1
	v_pk_fma_f32 v[20:21], v[106:107], v[92:93], v[4:5] op_sel_hi:[1,0,1]
	v_pk_fma_f32 v[22:23], v[106:107], v[92:93], v[6:7] op_sel:[0,1,0]
	v_pk_fma_f32 v[24:25], v[106:107], v[94:95], v[8:9] op_sel_hi:[1,0,1]
	v_pk_fma_f32 v[26:27], v[106:107], v[94:95], v[10:11] op_sel:[0,1,0]
	v_pk_fma_f32 v[28:29], v[106:107], v[96:97], v[12:13] op_sel_hi:[1,0,1]
	v_pk_fma_f32 v[30:31], v[106:107], v[96:97], v[14:15] op_sel:[0,1,0]
	v_pk_fma_f32 v[0:1], v[32:33], v[82:83], v[16:17] op_sel_hi:[1,0,1]
	v_pk_fma_f32 v[2:3], v[32:33], v[82:83], v[18:19] op_sel:[0,1,0]
	v_pk_fma_f32 v[4:5], v[32:33], v[84:85], v[20:21] op_sel_hi:[1,0,1]
	v_pk_fma_f32 v[6:7], v[32:33], v[84:85], v[22:23] op_sel:[0,1,0]
	v_pk_fma_f32 v[8:9], v[32:33], v[86:87], v[24:25] op_sel_hi:[1,0,1]
	v_pk_fma_f32 v[10:11], v[32:33], v[86:87], v[26:27] op_sel:[0,1,0]
	v_pk_fma_f32 v[12:13], v[32:33], v[88:89], v[28:29] op_sel_hi:[1,0,1]
	v_pk_fma_f32 v[14:15], v[32:33], v[88:89], v[30:31] op_sel:[0,1,0]
	s_waitcnt lgkmcnt(7)
	v_pk_mul_f32 v[32:33], v[0:1], v[40:41] op_sel_hi:[1,0]
	v_pk_mul_f32 v[36:37], v[0:1], v[98:99] op_sel_hi:[1,0]
	v_pk_mul_f32 v[34:35], v[2:3], v[40:41] op_sel:[0,1]
	v_pk_mul_f32 v[38:39], v[2:3], v[98:99] op_sel:[0,1]
	v_pk_fma_f32 v[32:33], v[4:5], v[42:43], v[32:33] op_sel_hi:[1,0,1]
	v_pk_fma_f32 v[36:37], v[4:5], v[100:101], v[36:37] op_sel_hi:[1,0,1]
	v_pk_fma_f32 v[34:35], v[6:7], v[42:43], v[34:35] op_sel:[0,1,0]
	v_pk_fma_f32 v[38:39], v[6:7], v[100:101], v[38:39] op_sel:[0,1,0]
	v_pk_fma_f32 v[32:33], v[8:9], v[44:45], v[32:33] op_sel_hi:[1,0,1]
	v_pk_fma_f32 v[36:37], v[8:9], v[102:103], v[36:37] op_sel_hi:[1,0,1]
	v_pk_fma_f32 v[34:35], v[10:11], v[44:45], v[34:35] op_sel:[0,1,0]
	v_pk_fma_f32 v[38:39], v[10:11], v[102:103], v[38:39] op_sel:[0,1,0]
	v_pk_fma_f32 v[32:33], v[12:13], v[46:47], v[32:33] op_sel_hi:[1,0,1]
	v_pk_fma_f32 v[36:37], v[12:13], v[104:105], v[36:37] op_sel_hi:[1,0,1]
	v_pk_fma_f32 v[34:35], v[14:15], v[46:47], v[34:35] op_sel:[0,1,0]
	v_pk_fma_f32 v[38:39], v[14:15], v[104:105], v[38:39] op_sel:[0,1,0]
	v_pk_add_f32 v[36:37], v[36:37], v[38:39]
	v_pk_add_f32 v[32:33], v[32:33], v[34:35]
	ds_write2st64_b32 v134, v36, v37 offset0:6 offset1:7
	ds_read_b128 v[74:77], v132 offset:8016
	ds_read_b128 v[78:81], v132 offset:8032
	ds_read_b128 v[82:85], v132 offset:8272
	ds_read_b128 v[86:89], v132 offset:8288
	ds_read_b128 v[90:93], v132 offset:8528
	ds_read_b128 v[94:97], v132 offset:8544
	ds_read_b128 v[98:101], v132 offset:8784
	ds_read_b128 v[102:105], v132 offset:8800
	ds_read_b64 v[106:107], v133 offset:9040
	s_waitcnt lgkmcnt(10)
	v_add_f32_dpp v32, v32, v32 row_half_mirror row_mask:0xf bank_mask:0xf bound_ctrl:1
	v_add_f32_dpp v33, v33, v33 row_half_mirror row_mask:0xf bank_mask:0xf bound_ctrl:1
	v_pk_fma_f32 v[16:17], v[72:73], v[56:57], v[0:1] op_sel_hi:[1,0,1]
	v_add_f32_dpp v32, v32, v32 quad_perm:[1,0,3,2] row_mask:0xf bank_mask:0xf bound_ctrl:1
	v_add_f32_dpp v33, v33, v33 quad_perm:[1,0,3,2] row_mask:0xf bank_mask:0xf bound_ctrl:1
	v_pk_fma_f32 v[18:19], v[72:73], v[56:57], v[2:3] op_sel:[0,1,0]
	v_add_f32_dpp v32, v32, v32 quad_perm:[2,3,0,1] row_mask:0xf bank_mask:0xf bound_ctrl:1
	v_add_f32_dpp v33, v33, v33 quad_perm:[2,3,0,1] row_mask:0xf bank_mask:0xf bound_ctrl:1
	v_pk_fma_f32 v[20:21], v[72:73], v[58:59], v[4:5] op_sel_hi:[1,0,1]
	v_pk_fma_f32 v[22:23], v[72:73], v[58:59], v[6:7] op_sel:[0,1,0]
	v_pk_fma_f32 v[24:25], v[72:73], v[60:61], v[8:9] op_sel_hi:[1,0,1]
	v_pk_fma_f32 v[26:27], v[72:73], v[60:61], v[10:11] op_sel:[0,1,0]
	v_pk_fma_f32 v[28:29], v[72:73], v[62:63], v[12:13] op_sel_hi:[1,0,1]
	v_pk_fma_f32 v[30:31], v[72:73], v[62:63], v[14:15] op_sel:[0,1,0]
	v_pk_fma_f32 v[0:1], v[32:33], v[48:49], v[16:17] op_sel_hi:[1,0,1]
	v_pk_fma_f32 v[2:3], v[32:33], v[48:49], v[18:19] op_sel:[0,1,0]
	v_pk_fma_f32 v[4:5], v[32:33], v[50:51], v[20:21] op_sel_hi:[1,0,1]
	v_pk_fma_f32 v[6:7], v[32:33], v[50:51], v[22:23] op_sel:[0,1,0]
	v_pk_fma_f32 v[8:9], v[32:33], v[52:53], v[24:25] op_sel_hi:[1,0,1]
	v_pk_fma_f32 v[10:11], v[32:33], v[52:53], v[26:27] op_sel:[0,1,0]
	v_pk_fma_f32 v[12:13], v[32:33], v[54:55], v[28:29] op_sel_hi:[1,0,1]
	v_pk_fma_f32 v[14:15], v[32:33], v[54:55], v[30:31] op_sel:[0,1,0]
	s_waitcnt lgkmcnt(7)
	v_pk_mul_f32 v[32:33], v[0:1], v[74:75] op_sel_hi:[1,0]
	v_pk_mul_f32 v[36:37], v[0:1], v[64:65] op_sel_hi:[1,0]
	v_pk_mul_f32 v[34:35], v[2:3], v[74:75] op_sel:[0,1]
	v_pk_mul_f32 v[38:39], v[2:3], v[64:65] op_sel:[0,1]
	v_pk_fma_f32 v[32:33], v[4:5], v[76:77], v[32:33] op_sel_hi:[1,0,1]
	v_pk_fma_f32 v[36:37], v[4:5], v[66:67], v[36:37] op_sel_hi:[1,0,1]
	v_pk_fma_f32 v[34:35], v[6:7], v[76:77], v[34:35] op_sel:[0,1,0]
	v_pk_fma_f32 v[38:39], v[6:7], v[66:67], v[38:39] op_sel:[0,1,0]
	v_pk_fma_f32 v[32:33], v[8:9], v[78:79], v[32:33] op_sel_hi:[1,0,1]
	v_pk_fma_f32 v[36:37], v[8:9], v[68:69], v[36:37] op_sel_hi:[1,0,1]
	v_pk_fma_f32 v[34:35], v[10:11], v[78:79], v[34:35] op_sel:[0,1,0]
	v_pk_fma_f32 v[38:39], v[10:11], v[68:69], v[38:39] op_sel:[0,1,0]
	v_pk_fma_f32 v[32:33], v[12:13], v[80:81], v[32:33] op_sel_hi:[1,0,1]
	v_pk_fma_f32 v[36:37], v[12:13], v[70:71], v[36:37] op_sel_hi:[1,0,1]
	v_pk_fma_f32 v[34:35], v[14:15], v[80:81], v[34:35] op_sel:[0,1,0]
	v_pk_fma_f32 v[38:39], v[14:15], v[70:71], v[38:39] op_sel:[0,1,0]
	v_pk_add_f32 v[36:37], v[36:37], v[38:39]
	v_pk_add_f32 v[32:33], v[32:33], v[34:35]
	ds_write2st64_b32 v134, v36, v37 offset0:8 offset1:9
	ds_read_b128 v[40:43], v132 offset:9568
	ds_read_b128 v[44:47], v132 offset:9584
	ds_read_b128 v[48:51], v132 offset:9824
	ds_read_b128 v[52:55], v132 offset:9840
	ds_read_b128 v[56:59], v132 offset:10080
	ds_read_b128 v[60:63], v132 offset:10096
	ds_read_b128 v[64:67], v132 offset:10336
	ds_read_b128 v[68:71], v132 offset:10352
	ds_read_b64 v[72:73], v133 offset:10592
	s_waitcnt lgkmcnt(10)
	v_add_f32_dpp v32, v32, v32 row_half_mirror row_mask:0xf bank_mask:0xf bound_ctrl:1
	v_add_f32_dpp v33, v33, v33 row_half_mirror row_mask:0xf bank_mask:0xf bound_ctrl:1
	v_pk_fma_f32 v[16:17], v[106:107], v[90:91], v[0:1] op_sel_hi:[1,0,1]
	v_add_f32_dpp v32, v32, v32 quad_perm:[1,0,3,2] row_mask:0xf bank_mask:0xf bound_ctrl:1
	v_add_f32_dpp v33, v33, v33 quad_perm:[1,0,3,2] row_mask:0xf bank_mask:0xf bound_ctrl:1
	v_pk_fma_f32 v[18:19], v[106:107], v[90:91], v[2:3] op_sel:[0,1,0]
	v_add_f32_dpp v32, v32, v32 quad_perm:[2,3,0,1] row_mask:0xf bank_mask:0xf bound_ctrl:1
	v_add_f32_dpp v33, v33, v33 quad_perm:[2,3,0,1] row_mask:0xf bank_mask:0xf bound_ctrl:1
	v_pk_fma_f32 v[20:21], v[106:107], v[92:93], v[4:5] op_sel_hi:[1,0,1]
	v_pk_fma_f32 v[22:23], v[106:107], v[92:93], v[6:7] op_sel:[0,1,0]
	v_pk_fma_f32 v[24:25], v[106:107], v[94:95], v[8:9] op_sel_hi:[1,0,1]
	v_pk_fma_f32 v[26:27], v[106:107], v[94:95], v[10:11] op_sel:[0,1,0]
	v_pk_fma_f32 v[28:29], v[106:107], v[96:97], v[12:13] op_sel_hi:[1,0,1]
	v_pk_fma_f32 v[30:31], v[106:107], v[96:97], v[14:15] op_sel:[0,1,0]
	v_pk_fma_f32 v[0:1], v[32:33], v[82:83], v[16:17] op_sel_hi:[1,0,1]
	v_pk_fma_f32 v[2:3], v[32:33], v[82:83], v[18:19] op_sel:[0,1,0]
	v_pk_fma_f32 v[4:5], v[32:33], v[84:85], v[20:21] op_sel_hi:[1,0,1]
	v_pk_fma_f32 v[6:7], v[32:33], v[84:85], v[22:23] op_sel:[0,1,0]
	v_pk_fma_f32 v[8:9], v[32:33], v[86:87], v[24:25] op_sel_hi:[1,0,1]
	v_pk_fma_f32 v[10:11], v[32:33], v[86:87], v[26:27] op_sel:[0,1,0]
	v_pk_fma_f32 v[12:13], v[32:33], v[88:89], v[28:29] op_sel_hi:[1,0,1]
	v_pk_fma_f32 v[14:15], v[32:33], v[88:89], v[30:31] op_sel:[0,1,0]
	s_waitcnt lgkmcnt(7)
	v_pk_mul_f32 v[32:33], v[0:1], v[40:41] op_sel_hi:[1,0]
	v_pk_mul_f32 v[36:37], v[0:1], v[98:99] op_sel_hi:[1,0]
	v_pk_mul_f32 v[34:35], v[2:3], v[40:41] op_sel:[0,1]
	v_pk_mul_f32 v[38:39], v[2:3], v[98:99] op_sel:[0,1]
	v_pk_fma_f32 v[32:33], v[4:5], v[42:43], v[32:33] op_sel_hi:[1,0,1]
	v_pk_fma_f32 v[36:37], v[4:5], v[100:101], v[36:37] op_sel_hi:[1,0,1]
	v_pk_fma_f32 v[34:35], v[6:7], v[42:43], v[34:35] op_sel:[0,1,0]
	v_pk_fma_f32 v[38:39], v[6:7], v[100:101], v[38:39] op_sel:[0,1,0]
	v_pk_fma_f32 v[32:33], v[8:9], v[44:45], v[32:33] op_sel_hi:[1,0,1]
	v_pk_fma_f32 v[36:37], v[8:9], v[102:103], v[36:37] op_sel_hi:[1,0,1]
	v_pk_fma_f32 v[34:35], v[10:11], v[44:45], v[34:35] op_sel:[0,1,0]
	v_pk_fma_f32 v[38:39], v[10:11], v[102:103], v[38:39] op_sel:[0,1,0]
	v_pk_fma_f32 v[32:33], v[12:13], v[46:47], v[32:33] op_sel_hi:[1,0,1]
	v_pk_fma_f32 v[36:37], v[12:13], v[104:105], v[36:37] op_sel_hi:[1,0,1]
	v_pk_fma_f32 v[34:35], v[14:15], v[46:47], v[34:35] op_sel:[0,1,0]
	v_pk_fma_f32 v[38:39], v[14:15], v[104:105], v[38:39] op_sel:[0,1,0]
	v_pk_add_f32 v[36:37], v[36:37], v[38:39]
	v_pk_add_f32 v[32:33], v[32:33], v[34:35]
	ds_write2st64_b32 v134, v36, v37 offset0:10 offset1:11
	ds_read_b128 v[74:77], v132 offset:11120
	ds_read_b128 v[78:81], v132 offset:11136
	ds_read_b128 v[82:85], v132 offset:11376
	ds_read_b128 v[86:89], v132 offset:11392
	ds_read_b128 v[90:93], v132 offset:11632
	ds_read_b128 v[94:97], v132 offset:11648
	ds_read_b128 v[98:101], v132 offset:11888
	ds_read_b128 v[102:105], v132 offset:11904
	ds_read_b64 v[106:107], v133 offset:12144
	s_waitcnt lgkmcnt(10)
	v_add_f32_dpp v32, v32, v32 row_half_mirror row_mask:0xf bank_mask:0xf bound_ctrl:1
	v_add_f32_dpp v33, v33, v33 row_half_mirror row_mask:0xf bank_mask:0xf bound_ctrl:1
	v_pk_fma_f32 v[16:17], v[72:73], v[56:57], v[0:1] op_sel_hi:[1,0,1]
	v_add_f32_dpp v32, v32, v32 quad_perm:[1,0,3,2] row_mask:0xf bank_mask:0xf bound_ctrl:1
	v_add_f32_dpp v33, v33, v33 quad_perm:[1,0,3,2] row_mask:0xf bank_mask:0xf bound_ctrl:1
	v_pk_fma_f32 v[18:19], v[72:73], v[56:57], v[2:3] op_sel:[0,1,0]
	v_add_f32_dpp v32, v32, v32 quad_perm:[2,3,0,1] row_mask:0xf bank_mask:0xf bound_ctrl:1
	v_add_f32_dpp v33, v33, v33 quad_perm:[2,3,0,1] row_mask:0xf bank_mask:0xf bound_ctrl:1
	v_pk_fma_f32 v[20:21], v[72:73], v[58:59], v[4:5] op_sel_hi:[1,0,1]
	v_pk_fma_f32 v[22:23], v[72:73], v[58:59], v[6:7] op_sel:[0,1,0]
	v_pk_fma_f32 v[24:25], v[72:73], v[60:61], v[8:9] op_sel_hi:[1,0,1]
	v_pk_fma_f32 v[26:27], v[72:73], v[60:61], v[10:11] op_sel:[0,1,0]
	v_pk_fma_f32 v[28:29], v[72:73], v[62:63], v[12:13] op_sel_hi:[1,0,1]
	v_pk_fma_f32 v[30:31], v[72:73], v[62:63], v[14:15] op_sel:[0,1,0]
	v_pk_fma_f32 v[0:1], v[32:33], v[48:49], v[16:17] op_sel_hi:[1,0,1]
	v_pk_fma_f32 v[2:3], v[32:33], v[48:49], v[18:19] op_sel:[0,1,0]
	v_pk_fma_f32 v[4:5], v[32:33], v[50:51], v[20:21] op_sel_hi:[1,0,1]
	v_pk_fma_f32 v[6:7], v[32:33], v[50:51], v[22:23] op_sel:[0,1,0]
	v_pk_fma_f32 v[8:9], v[32:33], v[52:53], v[24:25] op_sel_hi:[1,0,1]
	v_pk_fma_f32 v[10:11], v[32:33], v[52:53], v[26:27] op_sel:[0,1,0]
	v_pk_fma_f32 v[12:13], v[32:33], v[54:55], v[28:29] op_sel_hi:[1,0,1]
	v_pk_fma_f32 v[14:15], v[32:33], v[54:55], v[30:31] op_sel:[0,1,0]
	s_waitcnt lgkmcnt(7)
	v_pk_mul_f32 v[32:33], v[0:1], v[74:75] op_sel_hi:[1,0]
	v_pk_mul_f32 v[36:37], v[0:1], v[64:65] op_sel_hi:[1,0]
	v_pk_mul_f32 v[34:35], v[2:3], v[74:75] op_sel:[0,1]
	v_pk_mul_f32 v[38:39], v[2:3], v[64:65] op_sel:[0,1]
	v_pk_fma_f32 v[32:33], v[4:5], v[76:77], v[32:33] op_sel_hi:[1,0,1]
	v_pk_fma_f32 v[36:37], v[4:5], v[66:67], v[36:37] op_sel_hi:[1,0,1]
	v_pk_fma_f32 v[34:35], v[6:7], v[76:77], v[34:35] op_sel:[0,1,0]
	v_pk_fma_f32 v[38:39], v[6:7], v[66:67], v[38:39] op_sel:[0,1,0]
	v_pk_fma_f32 v[32:33], v[8:9], v[78:79], v[32:33] op_sel_hi:[1,0,1]
	v_pk_fma_f32 v[36:37], v[8:9], v[68:69], v[36:37] op_sel_hi:[1,0,1]
	v_pk_fma_f32 v[34:35], v[10:11], v[78:79], v[34:35] op_sel:[0,1,0]
	v_pk_fma_f32 v[38:39], v[10:11], v[68:69], v[38:39] op_sel:[0,1,0]
	v_pk_fma_f32 v[32:33], v[12:13], v[80:81], v[32:33] op_sel_hi:[1,0,1]
	v_pk_fma_f32 v[36:37], v[12:13], v[70:71], v[36:37] op_sel_hi:[1,0,1]
	v_pk_fma_f32 v[34:35], v[14:15], v[80:81], v[34:35] op_sel:[0,1,0]
	v_pk_fma_f32 v[38:39], v[14:15], v[70:71], v[38:39] op_sel:[0,1,0]
	v_pk_add_f32 v[36:37], v[36:37], v[38:39]
	v_pk_add_f32 v[32:33], v[32:33], v[34:35]
	ds_write2st64_b32 v134, v36, v37 offset0:12 offset1:13
	ds_read_b128 v[40:43], v132 offset:12672
	ds_read_b128 v[44:47], v132 offset:12688
	ds_read_b128 v[48:51], v132 offset:12928
	ds_read_b128 v[52:55], v132 offset:12944
	ds_read_b128 v[56:59], v132 offset:13184
	ds_read_b128 v[60:63], v132 offset:13200
	ds_read_b128 v[64:67], v132 offset:13440
	ds_read_b128 v[68:71], v132 offset:13456
	ds_read_b64 v[72:73], v133 offset:13696
	s_waitcnt lgkmcnt(10)
	v_add_f32_dpp v32, v32, v32 row_half_mirror row_mask:0xf bank_mask:0xf bound_ctrl:1
	v_add_f32_dpp v33, v33, v33 row_half_mirror row_mask:0xf bank_mask:0xf bound_ctrl:1
	v_pk_fma_f32 v[16:17], v[106:107], v[90:91], v[0:1] op_sel_hi:[1,0,1]
	v_add_f32_dpp v32, v32, v32 quad_perm:[1,0,3,2] row_mask:0xf bank_mask:0xf bound_ctrl:1
	v_add_f32_dpp v33, v33, v33 quad_perm:[1,0,3,2] row_mask:0xf bank_mask:0xf bound_ctrl:1
	v_pk_fma_f32 v[18:19], v[106:107], v[90:91], v[2:3] op_sel:[0,1,0]
	v_add_f32_dpp v32, v32, v32 quad_perm:[2,3,0,1] row_mask:0xf bank_mask:0xf bound_ctrl:1
	v_add_f32_dpp v33, v33, v33 quad_perm:[2,3,0,1] row_mask:0xf bank_mask:0xf bound_ctrl:1
	v_pk_fma_f32 v[20:21], v[106:107], v[92:93], v[4:5] op_sel_hi:[1,0,1]
	v_pk_fma_f32 v[22:23], v[106:107], v[92:93], v[6:7] op_sel:[0,1,0]
	v_pk_fma_f32 v[24:25], v[106:107], v[94:95], v[8:9] op_sel_hi:[1,0,1]
	v_pk_fma_f32 v[26:27], v[106:107], v[94:95], v[10:11] op_sel:[0,1,0]
	v_pk_fma_f32 v[28:29], v[106:107], v[96:97], v[12:13] op_sel_hi:[1,0,1]
	v_pk_fma_f32 v[30:31], v[106:107], v[96:97], v[14:15] op_sel:[0,1,0]
	v_pk_fma_f32 v[0:1], v[32:33], v[82:83], v[16:17] op_sel_hi:[1,0,1]
	v_pk_fma_f32 v[2:3], v[32:33], v[82:83], v[18:19] op_sel:[0,1,0]
	v_pk_fma_f32 v[4:5], v[32:33], v[84:85], v[20:21] op_sel_hi:[1,0,1]
	v_pk_fma_f32 v[6:7], v[32:33], v[84:85], v[22:23] op_sel:[0,1,0]
	v_pk_fma_f32 v[8:9], v[32:33], v[86:87], v[24:25] op_sel_hi:[1,0,1]
	v_pk_fma_f32 v[10:11], v[32:33], v[86:87], v[26:27] op_sel:[0,1,0]
	v_pk_fma_f32 v[12:13], v[32:33], v[88:89], v[28:29] op_sel_hi:[1,0,1]
	v_pk_fma_f32 v[14:15], v[32:33], v[88:89], v[30:31] op_sel:[0,1,0]
	s_waitcnt lgkmcnt(7)
	v_pk_mul_f32 v[32:33], v[0:1], v[40:41] op_sel_hi:[1,0]
	v_pk_mul_f32 v[36:37], v[0:1], v[98:99] op_sel_hi:[1,0]
	v_pk_mul_f32 v[34:35], v[2:3], v[40:41] op_sel:[0,1]
	v_pk_mul_f32 v[38:39], v[2:3], v[98:99] op_sel:[0,1]
	v_pk_fma_f32 v[32:33], v[4:5], v[42:43], v[32:33] op_sel_hi:[1,0,1]
	v_pk_fma_f32 v[36:37], v[4:5], v[100:101], v[36:37] op_sel_hi:[1,0,1]
	v_pk_fma_f32 v[34:35], v[6:7], v[42:43], v[34:35] op_sel:[0,1,0]
	v_pk_fma_f32 v[38:39], v[6:7], v[100:101], v[38:39] op_sel:[0,1,0]
	v_pk_fma_f32 v[32:33], v[8:9], v[44:45], v[32:33] op_sel_hi:[1,0,1]
	v_pk_fma_f32 v[36:37], v[8:9], v[102:103], v[36:37] op_sel_hi:[1,0,1]
	v_pk_fma_f32 v[34:35], v[10:11], v[44:45], v[34:35] op_sel:[0,1,0]
	v_pk_fma_f32 v[38:39], v[10:11], v[102:103], v[38:39] op_sel:[0,1,0]
	v_pk_fma_f32 v[32:33], v[12:13], v[46:47], v[32:33] op_sel_hi:[1,0,1]
	v_pk_fma_f32 v[36:37], v[12:13], v[104:105], v[36:37] op_sel_hi:[1,0,1]
	v_pk_fma_f32 v[34:35], v[14:15], v[46:47], v[34:35] op_sel:[0,1,0]
	v_pk_fma_f32 v[38:39], v[14:15], v[104:105], v[38:39] op_sel:[0,1,0]
	v_pk_add_f32 v[36:37], v[36:37], v[38:39]
	v_pk_add_f32 v[32:33], v[32:33], v[34:35]
	ds_write2st64_b32 v134, v36, v37 offset0:14 offset1:15
	ds_read_b128 v[74:77], v132 offset:14224
	ds_read_b128 v[78:81], v132 offset:14240
	ds_read_b128 v[82:85], v132 offset:14480
	ds_read_b128 v[86:89], v132 offset:14496
	ds_read_b128 v[90:93], v132 offset:14736
	ds_read_b128 v[94:97], v132 offset:14752
	ds_read_b128 v[98:101], v132 offset:14992
	ds_read_b128 v[102:105], v132 offset:15008
	ds_read_b64 v[106:107], v133 offset:15248
	ds_read_b128 v[116:119], v135
	ds_read_b128 v[120:123], v135 offset:16
	ds_read_b128 v[124:127], v135 offset:2048
	ds_read_b128 v[128:131], v135 offset:2064
	s_waitcnt lgkmcnt(14)
	v_add_f32_dpp v32, v32, v32 row_half_mirror row_mask:0xf bank_mask:0xf bound_ctrl:1
	v_add_f32_dpp v33, v33, v33 row_half_mirror row_mask:0xf bank_mask:0xf bound_ctrl:1
	v_pk_fma_f32 v[16:17], v[72:73], v[56:57], v[0:1] op_sel_hi:[1,0,1]
	v_add_f32_dpp v32, v32, v32 quad_perm:[1,0,3,2] row_mask:0xf bank_mask:0xf bound_ctrl:1
	v_add_f32_dpp v33, v33, v33 quad_perm:[1,0,3,2] row_mask:0xf bank_mask:0xf bound_ctrl:1
	v_pk_fma_f32 v[18:19], v[72:73], v[56:57], v[2:3] op_sel:[0,1,0]
	v_add_f32_dpp v32, v32, v32 quad_perm:[2,3,0,1] row_mask:0xf bank_mask:0xf bound_ctrl:1
	v_add_f32_dpp v33, v33, v33 quad_perm:[2,3,0,1] row_mask:0xf bank_mask:0xf bound_ctrl:1
	v_pk_fma_f32 v[20:21], v[72:73], v[58:59], v[4:5] op_sel_hi:[1,0,1]
	v_pk_fma_f32 v[22:23], v[72:73], v[58:59], v[6:7] op_sel:[0,1,0]
	v_pk_fma_f32 v[24:25], v[72:73], v[60:61], v[8:9] op_sel_hi:[1,0,1]
	v_pk_fma_f32 v[26:27], v[72:73], v[60:61], v[10:11] op_sel:[0,1,0]
	v_pk_fma_f32 v[28:29], v[72:73], v[62:63], v[12:13] op_sel_hi:[1,0,1]
	v_pk_fma_f32 v[30:31], v[72:73], v[62:63], v[14:15] op_sel:[0,1,0]
	v_pk_fma_f32 v[0:1], v[32:33], v[48:49], v[16:17] op_sel_hi:[1,0,1]
	v_pk_fma_f32 v[2:3], v[32:33], v[48:49], v[18:19] op_sel:[0,1,0]
	v_pk_fma_f32 v[4:5], v[32:33], v[50:51], v[20:21] op_sel_hi:[1,0,1]
	v_pk_fma_f32 v[6:7], v[32:33], v[50:51], v[22:23] op_sel:[0,1,0]
	v_pk_fma_f32 v[8:9], v[32:33], v[52:53], v[24:25] op_sel_hi:[1,0,1]
	v_pk_fma_f32 v[10:11], v[32:33], v[52:53], v[26:27] op_sel:[0,1,0]
	v_pk_fma_f32 v[12:13], v[32:33], v[54:55], v[28:29] op_sel_hi:[1,0,1]
	v_pk_fma_f32 v[14:15], v[32:33], v[54:55], v[30:31] op_sel:[0,1,0]
	s_waitcnt lgkmcnt(0)
	v_pk_add_f32 v[116:117], v[116:117], v[118:119]
	v_pk_add_f32 v[120:121], v[120:121], v[122:123]
	v_pk_add_f32 v[124:125], v[124:125], v[126:127]
	v_pk_add_f32 v[128:129], v[128:129], v[130:131]
	v_pk_add_f32 v[116:117], v[116:117], v[120:121]
	v_pk_add_f32 v[124:125], v[124:125], v[128:129]
	v_add_f32_e32 v116, v116, v117
	v_add_f32_e32 v124, v124, v125
	global_atomic_add_f32 v[136:137], v116, off
	global_atomic_add_f32 v[138:139], v124, off
	v_lshl_add_u64 v[136:137], v[136:137], 0, s[38:39]
	v_lshl_add_u64 v[138:139], v[138:139], 0, s[38:39]
	s_waitcnt lgkmcnt(7)
	v_pk_mul_f32 v[32:33], v[0:1], v[74:75] op_sel_hi:[1,0]
	v_pk_mul_f32 v[36:37], v[0:1], v[64:65] op_sel_hi:[1,0]
	v_pk_mul_f32 v[34:35], v[2:3], v[74:75] op_sel:[0,1]
	v_pk_mul_f32 v[38:39], v[2:3], v[64:65] op_sel:[0,1]
	v_pk_fma_f32 v[32:33], v[4:5], v[76:77], v[32:33] op_sel_hi:[1,0,1]
	v_pk_fma_f32 v[36:37], v[4:5], v[66:67], v[36:37] op_sel_hi:[1,0,1]
	v_pk_fma_f32 v[34:35], v[6:7], v[76:77], v[34:35] op_sel:[0,1,0]
	v_pk_fma_f32 v[38:39], v[6:7], v[66:67], v[38:39] op_sel:[0,1,0]
	v_pk_fma_f32 v[32:33], v[8:9], v[78:79], v[32:33] op_sel_hi:[1,0,1]
	v_pk_fma_f32 v[36:37], v[8:9], v[68:69], v[36:37] op_sel_hi:[1,0,1]
	v_pk_fma_f32 v[34:35], v[10:11], v[78:79], v[34:35] op_sel:[0,1,0]
	v_pk_fma_f32 v[38:39], v[10:11], v[68:69], v[38:39] op_sel:[0,1,0]
	v_pk_fma_f32 v[32:33], v[12:13], v[80:81], v[32:33] op_sel_hi:[1,0,1]
	v_pk_fma_f32 v[36:37], v[12:13], v[70:71], v[36:37] op_sel_hi:[1,0,1]
	v_pk_fma_f32 v[34:35], v[14:15], v[80:81], v[34:35] op_sel:[0,1,0]
	v_pk_fma_f32 v[38:39], v[14:15], v[70:71], v[38:39] op_sel:[0,1,0]
	v_pk_add_f32 v[36:37], v[36:37], v[38:39]
	v_pk_add_f32 v[32:33], v[32:33], v[34:35]
	ds_write2st64_b32 v134, v36, v37 offset0:0 offset1:1
	ds_read_b128 v[40:43], v132 offset:15776
	ds_read_b128 v[44:47], v132 offset:15792
	ds_read_b128 v[48:51], v132 offset:16032
	ds_read_b128 v[52:55], v132 offset:16048
	ds_read_b128 v[56:59], v132 offset:16288
	ds_read_b128 v[60:63], v132 offset:16304
	ds_read_b128 v[64:67], v132 offset:16544
	ds_read_b128 v[68:71], v132 offset:16560
	ds_read_b64 v[72:73], v133 offset:16800
	s_waitcnt lgkmcnt(10)
	v_add_f32_dpp v32, v32, v32 row_half_mirror row_mask:0xf bank_mask:0xf bound_ctrl:1
	v_add_f32_dpp v33, v33, v33 row_half_mirror row_mask:0xf bank_mask:0xf bound_ctrl:1
	v_pk_fma_f32 v[16:17], v[106:107], v[90:91], v[0:1] op_sel_hi:[1,0,1]
	v_add_f32_dpp v32, v32, v32 quad_perm:[1,0,3,2] row_mask:0xf bank_mask:0xf bound_ctrl:1
	v_add_f32_dpp v33, v33, v33 quad_perm:[1,0,3,2] row_mask:0xf bank_mask:0xf bound_ctrl:1
	v_pk_fma_f32 v[18:19], v[106:107], v[90:91], v[2:3] op_sel:[0,1,0]
	v_add_f32_dpp v32, v32, v32 quad_perm:[2,3,0,1] row_mask:0xf bank_mask:0xf bound_ctrl:1
	v_add_f32_dpp v33, v33, v33 quad_perm:[2,3,0,1] row_mask:0xf bank_mask:0xf bound_ctrl:1
	v_pk_fma_f32 v[20:21], v[106:107], v[92:93], v[4:5] op_sel_hi:[1,0,1]
	v_pk_fma_f32 v[22:23], v[106:107], v[92:93], v[6:7] op_sel:[0,1,0]
	v_pk_fma_f32 v[24:25], v[106:107], v[94:95], v[8:9] op_sel_hi:[1,0,1]
	v_pk_fma_f32 v[26:27], v[106:107], v[94:95], v[10:11] op_sel:[0,1,0]
	v_pk_fma_f32 v[28:29], v[106:107], v[96:97], v[12:13] op_sel_hi:[1,0,1]
	v_pk_fma_f32 v[30:31], v[106:107], v[96:97], v[14:15] op_sel:[0,1,0]
	v_pk_fma_f32 v[0:1], v[32:33], v[82:83], v[16:17] op_sel_hi:[1,0,1]
	v_pk_fma_f32 v[2:3], v[32:33], v[82:83], v[18:19] op_sel:[0,1,0]
	v_pk_fma_f32 v[4:5], v[32:33], v[84:85], v[20:21] op_sel_hi:[1,0,1]
	v_pk_fma_f32 v[6:7], v[32:33], v[84:85], v[22:23] op_sel:[0,1,0]
	v_pk_fma_f32 v[8:9], v[32:33], v[86:87], v[24:25] op_sel_hi:[1,0,1]
	v_pk_fma_f32 v[10:11], v[32:33], v[86:87], v[26:27] op_sel:[0,1,0]
	v_pk_fma_f32 v[12:13], v[32:33], v[88:89], v[28:29] op_sel_hi:[1,0,1]
	v_pk_fma_f32 v[14:15], v[32:33], v[88:89], v[30:31] op_sel:[0,1,0]
	s_waitcnt lgkmcnt(7)
	v_pk_mul_f32 v[32:33], v[0:1], v[40:41] op_sel_hi:[1,0]
	v_pk_mul_f32 v[36:37], v[0:1], v[98:99] op_sel_hi:[1,0]
	v_pk_mul_f32 v[34:35], v[2:3], v[40:41] op_sel:[0,1]
	v_pk_mul_f32 v[38:39], v[2:3], v[98:99] op_sel:[0,1]
	v_pk_fma_f32 v[32:33], v[4:5], v[42:43], v[32:33] op_sel_hi:[1,0,1]
	v_pk_fma_f32 v[36:37], v[4:5], v[100:101], v[36:37] op_sel_hi:[1,0,1]
	v_pk_fma_f32 v[34:35], v[6:7], v[42:43], v[34:35] op_sel:[0,1,0]
	v_pk_fma_f32 v[38:39], v[6:7], v[100:101], v[38:39] op_sel:[0,1,0]
	v_pk_fma_f32 v[32:33], v[8:9], v[44:45], v[32:33] op_sel_hi:[1,0,1]
	v_pk_fma_f32 v[36:37], v[8:9], v[102:103], v[36:37] op_sel_hi:[1,0,1]
	v_pk_fma_f32 v[34:35], v[10:11], v[44:45], v[34:35] op_sel:[0,1,0]
	v_pk_fma_f32 v[38:39], v[10:11], v[102:103], v[38:39] op_sel:[0,1,0]
	v_pk_fma_f32 v[32:33], v[12:13], v[46:47], v[32:33] op_sel_hi:[1,0,1]
	v_pk_fma_f32 v[36:37], v[12:13], v[104:105], v[36:37] op_sel_hi:[1,0,1]
	v_pk_fma_f32 v[34:35], v[14:15], v[46:47], v[34:35] op_sel:[0,1,0]
	v_pk_fma_f32 v[38:39], v[14:15], v[104:105], v[38:39] op_sel:[0,1,0]
	v_pk_add_f32 v[36:37], v[36:37], v[38:39]
	v_pk_add_f32 v[32:33], v[32:33], v[34:35]
	ds_write2st64_b32 v134, v36, v37 offset0:2 offset1:3
	ds_read_b128 v[74:77], v132 offset:17328
	ds_read_b128 v[78:81], v132 offset:17344
	ds_read_b128 v[82:85], v132 offset:17584
	ds_read_b128 v[86:89], v132 offset:17600
	ds_read_b128 v[90:93], v132 offset:17840
	ds_read_b128 v[94:97], v132 offset:17856
	ds_read_b128 v[98:101], v132 offset:18096
	ds_read_b128 v[102:105], v132 offset:18112
	ds_read_b64 v[106:107], v133 offset:18352
	s_waitcnt lgkmcnt(10)
	v_add_f32_dpp v32, v32, v32 row_half_mirror row_mask:0xf bank_mask:0xf bound_ctrl:1
	v_add_f32_dpp v33, v33, v33 row_half_mirror row_mask:0xf bank_mask:0xf bound_ctrl:1
	v_pk_fma_f32 v[16:17], v[72:73], v[56:57], v[0:1] op_sel_hi:[1,0,1]
	v_add_f32_dpp v32, v32, v32 quad_perm:[1,0,3,2] row_mask:0xf bank_mask:0xf bound_ctrl:1
	v_add_f32_dpp v33, v33, v33 quad_perm:[1,0,3,2] row_mask:0xf bank_mask:0xf bound_ctrl:1
	v_pk_fma_f32 v[18:19], v[72:73], v[56:57], v[2:3] op_sel:[0,1,0]
	v_add_f32_dpp v32, v32, v32 quad_perm:[2,3,0,1] row_mask:0xf bank_mask:0xf bound_ctrl:1
	v_add_f32_dpp v33, v33, v33 quad_perm:[2,3,0,1] row_mask:0xf bank_mask:0xf bound_ctrl:1
	v_pk_fma_f32 v[20:21], v[72:73], v[58:59], v[4:5] op_sel_hi:[1,0,1]
	v_pk_fma_f32 v[22:23], v[72:73], v[58:59], v[6:7] op_sel:[0,1,0]
	v_pk_fma_f32 v[24:25], v[72:73], v[60:61], v[8:9] op_sel_hi:[1,0,1]
	v_pk_fma_f32 v[26:27], v[72:73], v[60:61], v[10:11] op_sel:[0,1,0]
	v_pk_fma_f32 v[28:29], v[72:73], v[62:63], v[12:13] op_sel_hi:[1,0,1]
	v_pk_fma_f32 v[30:31], v[72:73], v[62:63], v[14:15] op_sel:[0,1,0]
	v_pk_fma_f32 v[0:1], v[32:33], v[48:49], v[16:17] op_sel_hi:[1,0,1]
	v_pk_fma_f32 v[2:3], v[32:33], v[48:49], v[18:19] op_sel:[0,1,0]
	v_pk_fma_f32 v[4:5], v[32:33], v[50:51], v[20:21] op_sel_hi:[1,0,1]
	v_pk_fma_f32 v[6:7], v[32:33], v[50:51], v[22:23] op_sel:[0,1,0]
	v_pk_fma_f32 v[8:9], v[32:33], v[52:53], v[24:25] op_sel_hi:[1,0,1]
	v_pk_fma_f32 v[10:11], v[32:33], v[52:53], v[26:27] op_sel:[0,1,0]
	v_pk_fma_f32 v[12:13], v[32:33], v[54:55], v[28:29] op_sel_hi:[1,0,1]
	v_pk_fma_f32 v[14:15], v[32:33], v[54:55], v[30:31] op_sel:[0,1,0]
	s_waitcnt lgkmcnt(7)
	v_pk_mul_f32 v[32:33], v[0:1], v[74:75] op_sel_hi:[1,0]
	v_pk_mul_f32 v[36:37], v[0:1], v[64:65] op_sel_hi:[1,0]
	v_pk_mul_f32 v[34:35], v[2:3], v[74:75] op_sel:[0,1]
	v_pk_mul_f32 v[38:39], v[2:3], v[64:65] op_sel:[0,1]
	v_pk_fma_f32 v[32:33], v[4:5], v[76:77], v[32:33] op_sel_hi:[1,0,1]
	v_pk_fma_f32 v[36:37], v[4:5], v[66:67], v[36:37] op_sel_hi:[1,0,1]
	v_pk_fma_f32 v[34:35], v[6:7], v[76:77], v[34:35] op_sel:[0,1,0]
	v_pk_fma_f32 v[38:39], v[6:7], v[66:67], v[38:39] op_sel:[0,1,0]
	v_pk_fma_f32 v[32:33], v[8:9], v[78:79], v[32:33] op_sel_hi:[1,0,1]
	v_pk_fma_f32 v[36:37], v[8:9], v[68:69], v[36:37] op_sel_hi:[1,0,1]
	v_pk_fma_f32 v[34:35], v[10:11], v[78:79], v[34:35] op_sel:[0,1,0]
	v_pk_fma_f32 v[38:39], v[10:11], v[68:69], v[38:39] op_sel:[0,1,0]
	v_pk_fma_f32 v[32:33], v[12:13], v[80:81], v[32:33] op_sel_hi:[1,0,1]
	v_pk_fma_f32 v[36:37], v[12:13], v[70:71], v[36:37] op_sel_hi:[1,0,1]
	v_pk_fma_f32 v[34:35], v[14:15], v[80:81], v[34:35] op_sel:[0,1,0]
	v_pk_fma_f32 v[38:39], v[14:15], v[70:71], v[38:39] op_sel:[0,1,0]
	v_pk_add_f32 v[36:37], v[36:37], v[38:39]
	v_pk_add_f32 v[32:33], v[32:33], v[34:35]
	ds_write2st64_b32 v134, v36, v37 offset0:4 offset1:5
	ds_read_b128 v[40:43], v132 offset:18880
	ds_read_b128 v[44:47], v132 offset:18896
	ds_read_b128 v[48:51], v132 offset:19136
	ds_read_b128 v[52:55], v132 offset:19152
	ds_read_b128 v[56:59], v132 offset:19392
	ds_read_b128 v[60:63], v132 offset:19408
	ds_read_b128 v[64:67], v132 offset:19648
	ds_read_b128 v[68:71], v132 offset:19664
	ds_read_b64 v[72:73], v133 offset:19904
	s_waitcnt lgkmcnt(10)
	v_add_f32_dpp v32, v32, v32 row_half_mirror row_mask:0xf bank_mask:0xf bound_ctrl:1
	v_add_f32_dpp v33, v33, v33 row_half_mirror row_mask:0xf bank_mask:0xf bound_ctrl:1
	v_pk_fma_f32 v[16:17], v[106:107], v[90:91], v[0:1] op_sel_hi:[1,0,1]
	v_add_f32_dpp v32, v32, v32 quad_perm:[1,0,3,2] row_mask:0xf bank_mask:0xf bound_ctrl:1
	v_add_f32_dpp v33, v33, v33 quad_perm:[1,0,3,2] row_mask:0xf bank_mask:0xf bound_ctrl:1
	v_pk_fma_f32 v[18:19], v[106:107], v[90:91], v[2:3] op_sel:[0,1,0]
	v_add_f32_dpp v32, v32, v32 quad_perm:[2,3,0,1] row_mask:0xf bank_mask:0xf bound_ctrl:1
	v_add_f32_dpp v33, v33, v33 quad_perm:[2,3,0,1] row_mask:0xf bank_mask:0xf bound_ctrl:1
	v_pk_fma_f32 v[20:21], v[106:107], v[92:93], v[4:5] op_sel_hi:[1,0,1]
	v_pk_fma_f32 v[22:23], v[106:107], v[92:93], v[6:7] op_sel:[0,1,0]
	v_pk_fma_f32 v[24:25], v[106:107], v[94:95], v[8:9] op_sel_hi:[1,0,1]
	v_pk_fma_f32 v[26:27], v[106:107], v[94:95], v[10:11] op_sel:[0,1,0]
	v_pk_fma_f32 v[28:29], v[106:107], v[96:97], v[12:13] op_sel_hi:[1,0,1]
	v_pk_fma_f32 v[30:31], v[106:107], v[96:97], v[14:15] op_sel:[0,1,0]
	v_pk_fma_f32 v[0:1], v[32:33], v[82:83], v[16:17] op_sel_hi:[1,0,1]
	v_pk_fma_f32 v[2:3], v[32:33], v[82:83], v[18:19] op_sel:[0,1,0]
	v_pk_fma_f32 v[4:5], v[32:33], v[84:85], v[20:21] op_sel_hi:[1,0,1]
	v_pk_fma_f32 v[6:7], v[32:33], v[84:85], v[22:23] op_sel:[0,1,0]
	v_pk_fma_f32 v[8:9], v[32:33], v[86:87], v[24:25] op_sel_hi:[1,0,1]
	v_pk_fma_f32 v[10:11], v[32:33], v[86:87], v[26:27] op_sel:[0,1,0]
	v_pk_fma_f32 v[12:13], v[32:33], v[88:89], v[28:29] op_sel_hi:[1,0,1]
	v_pk_fma_f32 v[14:15], v[32:33], v[88:89], v[30:31] op_sel:[0,1,0]
	s_waitcnt lgkmcnt(7)
	v_pk_mul_f32 v[32:33], v[0:1], v[40:41] op_sel_hi:[1,0]
	v_pk_mul_f32 v[36:37], v[0:1], v[98:99] op_sel_hi:[1,0]
	v_pk_mul_f32 v[34:35], v[2:3], v[40:41] op_sel:[0,1]
	v_pk_mul_f32 v[38:39], v[2:3], v[98:99] op_sel:[0,1]
	v_pk_fma_f32 v[32:33], v[4:5], v[42:43], v[32:33] op_sel_hi:[1,0,1]
	v_pk_fma_f32 v[36:37], v[4:5], v[100:101], v[36:37] op_sel_hi:[1,0,1]
	v_pk_fma_f32 v[34:35], v[6:7], v[42:43], v[34:35] op_sel:[0,1,0]
	v_pk_fma_f32 v[38:39], v[6:7], v[100:101], v[38:39] op_sel:[0,1,0]
	v_pk_fma_f32 v[32:33], v[8:9], v[44:45], v[32:33] op_sel_hi:[1,0,1]
	v_pk_fma_f32 v[36:37], v[8:9], v[102:103], v[36:37] op_sel_hi:[1,0,1]
	v_pk_fma_f32 v[34:35], v[10:11], v[44:45], v[34:35] op_sel:[0,1,0]
	v_pk_fma_f32 v[38:39], v[10:11], v[102:103], v[38:39] op_sel:[0,1,0]
	v_pk_fma_f32 v[32:33], v[12:13], v[46:47], v[32:33] op_sel_hi:[1,0,1]
	v_pk_fma_f32 v[36:37], v[12:13], v[104:105], v[36:37] op_sel_hi:[1,0,1]
	v_pk_fma_f32 v[34:35], v[14:15], v[46:47], v[34:35] op_sel:[0,1,0]
	v_pk_fma_f32 v[38:39], v[14:15], v[104:105], v[38:39] op_sel:[0,1,0]
	v_pk_add_f32 v[36:37], v[36:37], v[38:39]
	v_pk_add_f32 v[32:33], v[32:33], v[34:35]
	ds_write2st64_b32 v134, v36, v37 offset0:6 offset1:7
	ds_read_b128 v[74:77], v132 offset:20432
	ds_read_b128 v[78:81], v132 offset:20448
	ds_read_b128 v[82:85], v132 offset:20688
	ds_read_b128 v[86:89], v132 offset:20704
	ds_read_b128 v[90:93], v132 offset:20944
	ds_read_b128 v[94:97], v132 offset:20960
	ds_read_b128 v[98:101], v132 offset:21200
	ds_read_b128 v[102:105], v132 offset:21216
	ds_read_b64 v[106:107], v133 offset:21456
	s_waitcnt lgkmcnt(10)
	v_add_f32_dpp v32, v32, v32 row_half_mirror row_mask:0xf bank_mask:0xf bound_ctrl:1
	v_add_f32_dpp v33, v33, v33 row_half_mirror row_mask:0xf bank_mask:0xf bound_ctrl:1
	v_pk_fma_f32 v[16:17], v[72:73], v[56:57], v[0:1] op_sel_hi:[1,0,1]
	v_add_f32_dpp v32, v32, v32 quad_perm:[1,0,3,2] row_mask:0xf bank_mask:0xf bound_ctrl:1
	v_add_f32_dpp v33, v33, v33 quad_perm:[1,0,3,2] row_mask:0xf bank_mask:0xf bound_ctrl:1
	v_pk_fma_f32 v[18:19], v[72:73], v[56:57], v[2:3] op_sel:[0,1,0]
	v_add_f32_dpp v32, v32, v32 quad_perm:[2,3,0,1] row_mask:0xf bank_mask:0xf bound_ctrl:1
	v_add_f32_dpp v33, v33, v33 quad_perm:[2,3,0,1] row_mask:0xf bank_mask:0xf bound_ctrl:1
	v_pk_fma_f32 v[20:21], v[72:73], v[58:59], v[4:5] op_sel_hi:[1,0,1]
	v_pk_fma_f32 v[22:23], v[72:73], v[58:59], v[6:7] op_sel:[0,1,0]
	v_pk_fma_f32 v[24:25], v[72:73], v[60:61], v[8:9] op_sel_hi:[1,0,1]
	v_pk_fma_f32 v[26:27], v[72:73], v[60:61], v[10:11] op_sel:[0,1,0]
	v_pk_fma_f32 v[28:29], v[72:73], v[62:63], v[12:13] op_sel_hi:[1,0,1]
	v_pk_fma_f32 v[30:31], v[72:73], v[62:63], v[14:15] op_sel:[0,1,0]
	v_pk_fma_f32 v[0:1], v[32:33], v[48:49], v[16:17] op_sel_hi:[1,0,1]
	v_pk_fma_f32 v[2:3], v[32:33], v[48:49], v[18:19] op_sel:[0,1,0]
	v_pk_fma_f32 v[4:5], v[32:33], v[50:51], v[20:21] op_sel_hi:[1,0,1]
	v_pk_fma_f32 v[6:7], v[32:33], v[50:51], v[22:23] op_sel:[0,1,0]
	v_pk_fma_f32 v[8:9], v[32:33], v[52:53], v[24:25] op_sel_hi:[1,0,1]
	v_pk_fma_f32 v[10:11], v[32:33], v[52:53], v[26:27] op_sel:[0,1,0]
	v_pk_fma_f32 v[12:13], v[32:33], v[54:55], v[28:29] op_sel_hi:[1,0,1]
	v_pk_fma_f32 v[14:15], v[32:33], v[54:55], v[30:31] op_sel:[0,1,0]
	s_waitcnt lgkmcnt(7)
	v_pk_mul_f32 v[32:33], v[0:1], v[74:75] op_sel_hi:[1,0]
	v_pk_mul_f32 v[36:37], v[0:1], v[64:65] op_sel_hi:[1,0]
	v_pk_mul_f32 v[34:35], v[2:3], v[74:75] op_sel:[0,1]
	v_pk_mul_f32 v[38:39], v[2:3], v[64:65] op_sel:[0,1]
	v_pk_fma_f32 v[32:33], v[4:5], v[76:77], v[32:33] op_sel_hi:[1,0,1]
	v_pk_fma_f32 v[36:37], v[4:5], v[66:67], v[36:37] op_sel_hi:[1,0,1]
	v_pk_fma_f32 v[34:35], v[6:7], v[76:77], v[34:35] op_sel:[0,1,0]
	v_pk_fma_f32 v[38:39], v[6:7], v[66:67], v[38:39] op_sel:[0,1,0]
	v_pk_fma_f32 v[32:33], v[8:9], v[78:79], v[32:33] op_sel_hi:[1,0,1]
	v_pk_fma_f32 v[36:37], v[8:9], v[68:69], v[36:37] op_sel_hi:[1,0,1]
	v_pk_fma_f32 v[34:35], v[10:11], v[78:79], v[34:35] op_sel:[0,1,0]
	v_pk_fma_f32 v[38:39], v[10:11], v[68:69], v[38:39] op_sel:[0,1,0]
	v_pk_fma_f32 v[32:33], v[12:13], v[80:81], v[32:33] op_sel_hi:[1,0,1]
	v_pk_fma_f32 v[36:37], v[12:13], v[70:71], v[36:37] op_sel_hi:[1,0,1]
	v_pk_fma_f32 v[34:35], v[14:15], v[80:81], v[34:35] op_sel:[0,1,0]
	v_pk_fma_f32 v[38:39], v[14:15], v[70:71], v[38:39] op_sel:[0,1,0]
	v_pk_add_f32 v[36:37], v[36:37], v[38:39]
	v_pk_add_f32 v[32:33], v[32:33], v[34:35]
	ds_write2st64_b32 v134, v36, v37 offset0:8 offset1:9
	ds_read_b128 v[40:43], v132 offset:21984
	ds_read_b128 v[44:47], v132 offset:22000
	ds_read_b128 v[48:51], v132 offset:22240
	ds_read_b128 v[52:55], v132 offset:22256
	ds_read_b128 v[56:59], v132 offset:22496
	ds_read_b128 v[60:63], v132 offset:22512
	ds_read_b128 v[64:67], v132 offset:22752
	ds_read_b128 v[68:71], v132 offset:22768
	ds_read_b64 v[72:73], v133 offset:23008
	s_waitcnt lgkmcnt(10)
	v_add_f32_dpp v32, v32, v32 row_half_mirror row_mask:0xf bank_mask:0xf bound_ctrl:1
	v_add_f32_dpp v33, v33, v33 row_half_mirror row_mask:0xf bank_mask:0xf bound_ctrl:1
	v_pk_fma_f32 v[16:17], v[106:107], v[90:91], v[0:1] op_sel_hi:[1,0,1]
	v_add_f32_dpp v32, v32, v32 quad_perm:[1,0,3,2] row_mask:0xf bank_mask:0xf bound_ctrl:1
	v_add_f32_dpp v33, v33, v33 quad_perm:[1,0,3,2] row_mask:0xf bank_mask:0xf bound_ctrl:1
	v_pk_fma_f32 v[18:19], v[106:107], v[90:91], v[2:3] op_sel:[0,1,0]
	v_add_f32_dpp v32, v32, v32 quad_perm:[2,3,0,1] row_mask:0xf bank_mask:0xf bound_ctrl:1
	v_add_f32_dpp v33, v33, v33 quad_perm:[2,3,0,1] row_mask:0xf bank_mask:0xf bound_ctrl:1
	v_pk_fma_f32 v[20:21], v[106:107], v[92:93], v[4:5] op_sel_hi:[1,0,1]
	v_pk_fma_f32 v[22:23], v[106:107], v[92:93], v[6:7] op_sel:[0,1,0]
	v_pk_fma_f32 v[24:25], v[106:107], v[94:95], v[8:9] op_sel_hi:[1,0,1]
	v_pk_fma_f32 v[26:27], v[106:107], v[94:95], v[10:11] op_sel:[0,1,0]
	v_pk_fma_f32 v[28:29], v[106:107], v[96:97], v[12:13] op_sel_hi:[1,0,1]
	v_pk_fma_f32 v[30:31], v[106:107], v[96:97], v[14:15] op_sel:[0,1,0]
	v_pk_fma_f32 v[0:1], v[32:33], v[82:83], v[16:17] op_sel_hi:[1,0,1]
	v_pk_fma_f32 v[2:3], v[32:33], v[82:83], v[18:19] op_sel:[0,1,0]
	v_pk_fma_f32 v[4:5], v[32:33], v[84:85], v[20:21] op_sel_hi:[1,0,1]
	v_pk_fma_f32 v[6:7], v[32:33], v[84:85], v[22:23] op_sel:[0,1,0]
	v_pk_fma_f32 v[8:9], v[32:33], v[86:87], v[24:25] op_sel_hi:[1,0,1]
	v_pk_fma_f32 v[10:11], v[32:33], v[86:87], v[26:27] op_sel:[0,1,0]
	v_pk_fma_f32 v[12:13], v[32:33], v[88:89], v[28:29] op_sel_hi:[1,0,1]
	v_pk_fma_f32 v[14:15], v[32:33], v[88:89], v[30:31] op_sel:[0,1,0]
	s_waitcnt lgkmcnt(7)
	v_pk_mul_f32 v[32:33], v[0:1], v[40:41] op_sel_hi:[1,0]
	v_pk_mul_f32 v[36:37], v[0:1], v[98:99] op_sel_hi:[1,0]
	v_pk_mul_f32 v[34:35], v[2:3], v[40:41] op_sel:[0,1]
	v_pk_mul_f32 v[38:39], v[2:3], v[98:99] op_sel:[0,1]
	v_pk_fma_f32 v[32:33], v[4:5], v[42:43], v[32:33] op_sel_hi:[1,0,1]
	v_pk_fma_f32 v[36:37], v[4:5], v[100:101], v[36:37] op_sel_hi:[1,0,1]
	v_pk_fma_f32 v[34:35], v[6:7], v[42:43], v[34:35] op_sel:[0,1,0]
	v_pk_fma_f32 v[38:39], v[6:7], v[100:101], v[38:39] op_sel:[0,1,0]
	v_pk_fma_f32 v[32:33], v[8:9], v[44:45], v[32:33] op_sel_hi:[1,0,1]
	v_pk_fma_f32 v[36:37], v[8:9], v[102:103], v[36:37] op_sel_hi:[1,0,1]
	v_pk_fma_f32 v[34:35], v[10:11], v[44:45], v[34:35] op_sel:[0,1,0]
	v_pk_fma_f32 v[38:39], v[10:11], v[102:103], v[38:39] op_sel:[0,1,0]
	v_pk_fma_f32 v[32:33], v[12:13], v[46:47], v[32:33] op_sel_hi:[1,0,1]
	v_pk_fma_f32 v[36:37], v[12:13], v[104:105], v[36:37] op_sel_hi:[1,0,1]
	v_pk_fma_f32 v[34:35], v[14:15], v[46:47], v[34:35] op_sel:[0,1,0]
	v_pk_fma_f32 v[38:39], v[14:15], v[104:105], v[38:39] op_sel:[0,1,0]
	v_pk_add_f32 v[36:37], v[36:37], v[38:39]
	v_pk_add_f32 v[32:33], v[32:33], v[34:35]
	ds_write2st64_b32 v134, v36, v37 offset0:10 offset1:11
	ds_read_b128 v[74:77], v132 offset:23536
	ds_read_b128 v[78:81], v132 offset:23552
	ds_read_b128 v[82:85], v132 offset:23792
	ds_read_b128 v[86:89], v132 offset:23808
	ds_read_b128 v[90:93], v132 offset:24048
	ds_read_b128 v[94:97], v132 offset:24064
	ds_read_b128 v[98:101], v132 offset:24304
	ds_read_b128 v[102:105], v132 offset:24320
	ds_read_b64 v[106:107], v133 offset:24560
	s_waitcnt lgkmcnt(10)
	v_add_f32_dpp v32, v32, v32 row_half_mirror row_mask:0xf bank_mask:0xf bound_ctrl:1
	v_add_f32_dpp v33, v33, v33 row_half_mirror row_mask:0xf bank_mask:0xf bound_ctrl:1
	v_pk_fma_f32 v[16:17], v[72:73], v[56:57], v[0:1] op_sel_hi:[1,0,1]
	v_add_f32_dpp v32, v32, v32 quad_perm:[1,0,3,2] row_mask:0xf bank_mask:0xf bound_ctrl:1
	v_add_f32_dpp v33, v33, v33 quad_perm:[1,0,3,2] row_mask:0xf bank_mask:0xf bound_ctrl:1
	v_pk_fma_f32 v[18:19], v[72:73], v[56:57], v[2:3] op_sel:[0,1,0]
	v_add_f32_dpp v32, v32, v32 quad_perm:[2,3,0,1] row_mask:0xf bank_mask:0xf bound_ctrl:1
	v_add_f32_dpp v33, v33, v33 quad_perm:[2,3,0,1] row_mask:0xf bank_mask:0xf bound_ctrl:1
	v_pk_fma_f32 v[20:21], v[72:73], v[58:59], v[4:5] op_sel_hi:[1,0,1]
	v_pk_fma_f32 v[22:23], v[72:73], v[58:59], v[6:7] op_sel:[0,1,0]
	v_pk_fma_f32 v[24:25], v[72:73], v[60:61], v[8:9] op_sel_hi:[1,0,1]
	v_pk_fma_f32 v[26:27], v[72:73], v[60:61], v[10:11] op_sel:[0,1,0]
	v_pk_fma_f32 v[28:29], v[72:73], v[62:63], v[12:13] op_sel_hi:[1,0,1]
	v_pk_fma_f32 v[30:31], v[72:73], v[62:63], v[14:15] op_sel:[0,1,0]
	v_pk_fma_f32 v[0:1], v[32:33], v[48:49], v[16:17] op_sel_hi:[1,0,1]
	v_pk_fma_f32 v[2:3], v[32:33], v[48:49], v[18:19] op_sel:[0,1,0]
	v_pk_fma_f32 v[4:5], v[32:33], v[50:51], v[20:21] op_sel_hi:[1,0,1]
	v_pk_fma_f32 v[6:7], v[32:33], v[50:51], v[22:23] op_sel:[0,1,0]
	v_pk_fma_f32 v[8:9], v[32:33], v[52:53], v[24:25] op_sel_hi:[1,0,1]
	v_pk_fma_f32 v[10:11], v[32:33], v[52:53], v[26:27] op_sel:[0,1,0]
	v_pk_fma_f32 v[12:13], v[32:33], v[54:55], v[28:29] op_sel_hi:[1,0,1]
	v_pk_fma_f32 v[14:15], v[32:33], v[54:55], v[30:31] op_sel:[0,1,0]
	s_waitcnt lgkmcnt(7)
	v_pk_mul_f32 v[32:33], v[0:1], v[74:75] op_sel_hi:[1,0]
	v_pk_mul_f32 v[36:37], v[0:1], v[64:65] op_sel_hi:[1,0]
	v_pk_mul_f32 v[34:35], v[2:3], v[74:75] op_sel:[0,1]
	v_pk_mul_f32 v[38:39], v[2:3], v[64:65] op_sel:[0,1]
	v_pk_fma_f32 v[32:33], v[4:5], v[76:77], v[32:33] op_sel_hi:[1,0,1]
	v_pk_fma_f32 v[36:37], v[4:5], v[66:67], v[36:37] op_sel_hi:[1,0,1]
	v_pk_fma_f32 v[34:35], v[6:7], v[76:77], v[34:35] op_sel:[0,1,0]
	v_pk_fma_f32 v[38:39], v[6:7], v[66:67], v[38:39] op_sel:[0,1,0]
	v_pk_fma_f32 v[32:33], v[8:9], v[78:79], v[32:33] op_sel_hi:[1,0,1]
	v_pk_fma_f32 v[36:37], v[8:9], v[68:69], v[36:37] op_sel_hi:[1,0,1]
	v_pk_fma_f32 v[34:35], v[10:11], v[78:79], v[34:35] op_sel:[0,1,0]
	v_pk_fma_f32 v[38:39], v[10:11], v[68:69], v[38:39] op_sel:[0,1,0]
	v_pk_fma_f32 v[32:33], v[12:13], v[80:81], v[32:33] op_sel_hi:[1,0,1]
	v_pk_fma_f32 v[36:37], v[12:13], v[70:71], v[36:37] op_sel_hi:[1,0,1]
	v_pk_fma_f32 v[34:35], v[14:15], v[80:81], v[34:35] op_sel:[0,1,0]
	v_pk_fma_f32 v[38:39], v[14:15], v[70:71], v[38:39] op_sel:[0,1,0]
	v_pk_add_f32 v[36:37], v[36:37], v[38:39]
	v_pk_add_f32 v[32:33], v[32:33], v[34:35]
	ds_write2st64_b32 v134, v36, v37 offset0:12 offset1:13
	ds_read_b128 v[108:111], v132 offset:23280
	ds_read_b128 v[112:115], v132 offset:23296
	s_waitcnt lgkmcnt(3)
	v_add_f32_dpp v32, v32, v32 row_half_mirror row_mask:0xf bank_mask:0xf bound_ctrl:1
	v_add_f32_dpp v33, v33, v33 row_half_mirror row_mask:0xf bank_mask:0xf bound_ctrl:1
	v_pk_fma_f32 v[16:17], v[106:107], v[90:91], v[0:1] op_sel_hi:[1,0,1]
	v_add_f32_dpp v32, v32, v32 quad_perm:[1,0,3,2] row_mask:0xf bank_mask:0xf bound_ctrl:1
	v_add_f32_dpp v33, v33, v33 quad_perm:[1,0,3,2] row_mask:0xf bank_mask:0xf bound_ctrl:1
	v_pk_fma_f32 v[18:19], v[106:107], v[90:91], v[2:3] op_sel:[0,1,0]
	v_add_f32_dpp v32, v32, v32 quad_perm:[2,3,0,1] row_mask:0xf bank_mask:0xf bound_ctrl:1
	v_add_f32_dpp v33, v33, v33 quad_perm:[2,3,0,1] row_mask:0xf bank_mask:0xf bound_ctrl:1
	v_pk_fma_f32 v[20:21], v[106:107], v[92:93], v[4:5] op_sel_hi:[1,0,1]
	v_pk_fma_f32 v[22:23], v[106:107], v[92:93], v[6:7] op_sel:[0,1,0]
	v_pk_fma_f32 v[24:25], v[106:107], v[94:95], v[8:9] op_sel_hi:[1,0,1]
	v_pk_fma_f32 v[26:27], v[106:107], v[94:95], v[10:11] op_sel:[0,1,0]
	v_pk_fma_f32 v[28:29], v[106:107], v[96:97], v[12:13] op_sel_hi:[1,0,1]
	v_pk_fma_f32 v[30:31], v[106:107], v[96:97], v[14:15] op_sel:[0,1,0]
	v_pk_fma_f32 v[0:1], v[32:33], v[82:83], v[16:17] op_sel_hi:[1,0,1]
	v_pk_fma_f32 v[2:3], v[32:33], v[82:83], v[18:19] op_sel:[0,1,0]
	v_pk_fma_f32 v[4:5], v[32:33], v[84:85], v[20:21] op_sel_hi:[1,0,1]
	v_pk_fma_f32 v[6:7], v[32:33], v[84:85], v[22:23] op_sel:[0,1,0]
	v_pk_fma_f32 v[8:9], v[32:33], v[86:87], v[24:25] op_sel_hi:[1,0,1]
	v_pk_fma_f32 v[10:11], v[32:33], v[86:87], v[26:27] op_sel:[0,1,0]
	v_pk_fma_f32 v[12:13], v[32:33], v[88:89], v[28:29] op_sel_hi:[1,0,1]
	v_pk_fma_f32 v[14:15], v[32:33], v[88:89], v[30:31] op_sel:[0,1,0]
	v_pk_mul_f32 v[36:37], v[0:1], v[98:99] op_sel_hi:[1,0]
	v_pk_mul_f32 v[38:39], v[2:3], v[98:99] op_sel:[0,1]
	v_pk_fma_f32 v[36:37], v[4:5], v[100:101], v[36:37] op_sel_hi:[1,0,1]
	v_pk_fma_f32 v[38:39], v[6:7], v[100:101], v[38:39] op_sel:[0,1,0]
	v_pk_fma_f32 v[36:37], v[8:9], v[102:103], v[36:37] op_sel_hi:[1,0,1]
	v_pk_fma_f32 v[38:39], v[10:11], v[102:103], v[38:39] op_sel:[0,1,0]
	v_pk_fma_f32 v[36:37], v[12:13], v[104:105], v[36:37] op_sel_hi:[1,0,1]
	v_pk_fma_f32 v[38:39], v[14:15], v[104:105], v[38:39] op_sel:[0,1,0]
	v_pk_add_f32 v[36:37], v[36:37], v[38:39]
	ds_write2st64_b32 v134, v36, v37 offset0:14 offset1:15
	ds_read_b128 v[116:119], v135
	ds_read_b128 v[120:123], v135 offset:16
	ds_read_b128 v[124:127], v135 offset:2048
	ds_read_b128 v[128:131], v135 offset:2064
	s_waitcnt lgkmcnt(4)
	v_pk_mul_f32 v[0:1], v[0:1], v[108:109] op_sel_hi:[1,0]
	v_pk_mul_f32 v[2:3], v[2:3], v[108:109] op_sel:[0,1]
	v_pk_mul_f32 v[4:5], v[4:5], v[110:111] op_sel_hi:[1,0]
	v_pk_mul_f32 v[6:7], v[6:7], v[110:111] op_sel:[0,1]
	v_pk_mul_f32 v[8:9], v[8:9], v[112:113] op_sel_hi:[1,0]
	v_pk_mul_f32 v[10:11], v[10:11], v[112:113] op_sel:[0,1]
	v_pk_mul_f32 v[12:13], v[12:13], v[114:115] op_sel_hi:[1,0]
	v_pk_mul_f32 v[14:15], v[14:15], v[114:115] op_sel:[0,1]
	s_waitcnt lgkmcnt(0)
	v_pk_add_f32 v[116:117], v[116:117], v[118:119]
	v_pk_add_f32 v[120:121], v[120:121], v[122:123]
	v_pk_add_f32 v[124:125], v[124:125], v[126:127]
	v_pk_add_f32 v[128:129], v[128:129], v[130:131]
	v_pk_add_f32 v[116:117], v[116:117], v[120:121]
	v_pk_add_f32 v[124:125], v[124:125], v[128:129]
	v_add_f32_e32 v116, v116, v117
	v_add_f32_e32 v124, v124, v125
	global_atomic_add_f32 v[136:137], v116, off
	global_atomic_add_f32 v[138:139], v124, off
	v_lshl_add_u64 v[136:137], v[136:137], 0, s[38:39]
	v_lshl_add_u64 v[138:139], v[138:139], 0, s[38:39]
	s_xor_b32 s75, s75, 0x6100
	s_waitcnt lgkmcnt(0)
	s_barrier
	s_add_i32 s74, s74, 1
	s_cmp_lt_u32 s74, s73
	s_cbranch_scc1 .Lst_chunk
	s_cmp_eq_u32 s70, 0
	s_cbranch_scc1 .Lst_item_next
	v_mov_b32_e32 v164, v0
	v_mov_b32_e32 v172, v1
	v_mov_b32_e32 v165, v2
	v_mov_b32_e32 v173, v3
	v_mov_b32_e32 v166, v4
	v_mov_b32_e32 v174, v5
	v_mov_b32_e32 v167, v6
	v_mov_b32_e32 v175, v7
	v_mov_b32_e32 v168, v8
	v_mov_b32_e32 v176, v9
	v_mov_b32_e32 v169, v10
	v_mov_b32_e32 v177, v11
	v_mov_b32_e32 v170, v12
	v_mov_b32_e32 v178, v13
	v_mov_b32_e32 v171, v14
	v_mov_b32_e32 v179, v15
	s_add_u32 s4, s20, 0x9000000
	s_addc_u32 s5, s21, 0
	s_add_u32 s4, s4, s40
	s_addc_u32 s5, s5, s41
	v_lshl_add_u64 v[182:183], v[184:185], 0, s[4:5]
	global_store_dwordx4 v[182:183], v[164:167], off
	global_store_dwordx4 v[182:183], v[168:171], off offset:16
	global_store_dwordx4 v[182:183], v[172:175], off offset:256
	global_store_dwordx4 v[182:183], v[176:179], off offset:272
